# w21: w9 + GLA pre-pass gate loop LDS reads issued 12 ahead into a rotating register pool (counted lgkmcnt) + gla_seq step LDS reads hoisted in two batches
# speedup vs baseline: 1.0080x; 1.0080x over previous
; #define LAS __attribute__((address_space(3)))
; DI float log_sigmoid_(float x) { return fminf(x, 0.f) - __logf(1.f + __expf(-fabsf(x))); }
; DI f32x4 bf2x2(u32x2 q) { return (f32x4){__builtin_bit_cast(float, q.x << 16), __builtin_bit_cast(float, q.x & 0xffff0000u), __builtin_bit_cast(float, q.y << 16), __builtin_bit_cast(float, q.y & 0xffff0000u)}; }
; DI void gla_pre_item(Frame& F, int item, PreRegs& R, int nxt) {
;     ...
;     for (int i = 0; i < 4; ++i) { const int idx = tid + 512 * i, row = idx >> 5, c4 = idx & 31; *(LAS f32x4*)(QH + row * GLP + 4 * c4) = bf2x2(R.q[i]); *(LAS f32x4*)(KH + row * GLP + 4 * c4) = bf2x2(R.k[i]); }
;     if (tid < 256) { const int row = tid >> 2, c4 = tid & 3; *(LAS f32x4*)(GA + row * 16 + 4 * c4) = R.ga; }
;     float w2r[16];
; #pragma unroll
;     for (int r = 0; r < 16; ++r) w2r[r] = F.w_g2[r * 512 + h * 128 + kk];
;     const float b2 = F.b_g2[h * 128 + kk];
;     __syncthreads();
;     float cum[16]; float run = 0.f;
; #pragma unroll
;     for (int i = 0; i < 16; ++i) { const int t = 16 * tq + i; float x = b2;
; #pragma unroll
;         for (int r = 0; r < 16; ++r) x += GA[t * 16 + r] * w2r[r];
;         run += log_sigmoid_(x) * (1.f / 16.f); cum[i] = run; }
.LBB0_1020:
	s_waitcnt vmcnt(15)
	v_lshlrev_b32_e32 v6, 16, v30
	v_and_b32_e32 v7, 0xffff0000, v30
	v_lshlrev_b32_e32 v8, 16, v31
	v_and_b32_e32 v9, 0xffff0000, v31
	s_barrier
	ds_write_b128 v62, v[6:9]
	s_waitcnt vmcnt(14)
	v_lshlrev_b32_e32 v6, 16, v32
	v_and_b32_e32 v7, 0xffff0000, v32
	v_lshlrev_b32_e32 v8, 16, v33
	v_and_b32_e32 v9, 0xffff0000, v33
	ds_write_b128 v62, v[6:9] offset:33792
	s_waitcnt vmcnt(13)
	v_lshlrev_b32_e32 v6, 16, v34
	v_and_b32_e32 v7, 0xffff0000, v34
	v_lshlrev_b32_e32 v8, 16, v35
	v_and_b32_e32 v9, 0xffff0000, v35
	ds_write_b128 v64, v[6:9]
	s_waitcnt vmcnt(12)
	v_lshlrev_b32_e32 v6, 16, v36
	v_and_b32_e32 v7, 0xffff0000, v36
	v_lshlrev_b32_e32 v8, 16, v37
	v_and_b32_e32 v9, 0xffff0000, v37
	ds_write_b128 v64, v[6:9] offset:33792
	s_waitcnt vmcnt(11)
	v_lshlrev_b32_e32 v6, 16, v40
	v_and_b32_e32 v7, 0xffff0000, v40
	v_lshlrev_b32_e32 v8, 16, v41
	v_and_b32_e32 v9, 0xffff0000, v41
	ds_write_b128 v66, v[6:9]
	s_waitcnt vmcnt(10)
	v_lshlrev_b32_e32 v6, 16, v42
	v_and_b32_e32 v7, 0xffff0000, v42
	v_lshlrev_b32_e32 v8, 16, v43
	v_and_b32_e32 v9, 0xffff0000, v43
	ds_write_b128 v66, v[6:9] offset:33792
	s_waitcnt vmcnt(9)
	v_lshlrev_b32_e32 v6, 16, v44
	v_and_b32_e32 v7, 0xffff0000, v44
	v_lshlrev_b32_e32 v8, 16, v45
	v_and_b32_e32 v9, 0xffff0000, v45
	ds_write_b128 v68, v[6:9]
	s_waitcnt vmcnt(8)
	v_lshlrev_b32_e32 v6, 16, v46
	v_and_b32_e32 v7, 0xffff0000, v46
	v_lshlrev_b32_e32 v8, 16, v47
	v_and_b32_e32 v9, 0xffff0000, v47
	ds_write_b128 v68, v[6:9] offset:33792
	s_and_saveexec_b64 s[2:3], s[0:1]
	ds_write_b128 v15, v[2:5]
	s_or_b64 exec, exec, s[2:3]
	s_and_b32 s2, s33, 0x180
	v_or_b32_e32 v6, s2, v14
	v_readlane_b32 s80, v253, 23
	v_lshlrev_b32_e32 v38, 2, v6
	v_readlane_b32 s84, v253, 27
	v_readlane_b32 s85, v253, 28
	s_nop 4
	global_load_dword v120, v38, s[84:85]
	global_load_dword v121, v38, s[84:85] offset:2048
	v_lshl_add_u64 v[8:9], s[84:85], 0, v[38:39]
	v_add_co_u32_e32 v6, vcc, 0x1000, v8
	v_readlane_b32 s86, v253, 29
	s_nop 0
	v_addc_co_u32_e32 v7, vcc, 0, v9, vcc
	global_load_dword v122, v[6:7], off
	global_load_dword v123, v[6:7], off offset:2048
	v_add_co_u32_e32 v6, vcc, 0x2000, v8
	v_readlane_b32 s87, v253, 30
	s_nop 0
	v_addc_co_u32_e32 v7, vcc, 0, v9, vcc
	global_load_dword v10, v[6:7], off
	global_load_dword v11, v[6:7], off offset:2048
	v_add_co_u32_e32 v6, vcc, 0x3000, v8
	v_readlane_b32 s81, v253, 24
	s_nop 0
	v_addc_co_u32_e32 v7, vcc, 0, v9, vcc
	global_load_dword v118, v[6:7], off
	global_load_dword v119, v[6:7], off offset:2048
	v_add_co_u32_e32 v6, vcc, 0x4000, v8
	v_readlane_b32 s82, v253, 25
	s_nop 0
	v_addc_co_u32_e32 v7, vcc, 0, v9, vcc
	global_load_dword v19, v[6:7], off
	global_load_dword v103, v[6:7], off offset:2048
	v_add_co_u32_e32 v6, vcc, 0x5000, v8
	v_readlane_b32 s83, v253, 26
	s_nop 0
	v_addc_co_u32_e32 v7, vcc, 0, v9, vcc
	v_add_co_u32_e32 v124, vcc, 0x6000, v8
	global_load_dword v116, v[6:7], off
	global_load_dword v117, v[6:7], off offset:2048
	v_addc_co_u32_e32 v125, vcc, 0, v9, vcc
	global_load_dword v7, v[124:125], off
	global_load_dword v6, v[124:125], off offset:2048
	v_add_co_u32_e32 v124, vcc, 0x7000, v8
	v_readlane_b32 s88, v253, 31
	s_nop 0
	v_addc_co_u32_e32 v125, vcc, 0, v9, vcc
	global_load_dword v9, v[124:125], off
	global_load_dword v8, v[124:125], off offset:2048
	s_nop 0
	global_load_dword v38, v38, s[86:87]
	s_waitcnt lgkmcnt(0)
	s_barrier
	ds_read_b128 v[124:127], v63
	ds_read_b128 v[128:131], v63 offset:16
	ds_read_b128 v[132:135], v63 offset:32
	ds_read_b128 v[136:139], v63 offset:48
	v_readlane_b32 s89, v253, 32
	v_readlane_b32 s90, v253, 33
	v_readlane_b32 s91, v253, 34
	v_readlane_b32 s92, v253, 35
	v_readlane_b32 s93, v253, 36
	v_readlane_b32 s94, v253, 37
	v_readlane_b32 s95, v253, 38
	s_waitcnt vmcnt(0) lgkmcnt(3)
	v_fma_f32 v124, v120, v124, v38
	v_fmac_f32_e32 v124, v121, v125
	v_fmac_f32_e32 v124, v122, v126
	v_fmac_f32_e32 v124, v123, v127
	s_waitcnt lgkmcnt(2)
	v_fmac_f32_e32 v124, v10, v128
	v_fmac_f32_e32 v124, v11, v129
	v_fmac_f32_e32 v124, v118, v130
	v_fmac_f32_e32 v124, v119, v131
	s_waitcnt lgkmcnt(1)
	v_fmac_f32_e32 v124, v19, v132
	v_fmac_f32_e32 v124, v103, v133
	v_fmac_f32_e32 v124, v116, v134
	v_fmac_f32_e32 v124, v117, v135
	s_waitcnt lgkmcnt(0)
	v_fmac_f32_e32 v124, v7, v136
	v_fmac_f32_e32 v124, v6, v137
	v_fmac_f32_e32 v124, v9, v138
	v_fmac_f32_e32 v124, v8, v139
	v_min_f32_e32 v125, 0, v124
	v_mul_f32_e64 v124, |v124|, s69
	v_exp_f32_e32 v124, v124
	s_nop 0
	v_add_f32_e32 v124, 1.0, v124
	v_cmp_gt_f32_e32 vcc, s70, v124
	s_nop 1
	v_cndmask_b32_e64 v126, 0, 32, vcc
	v_ldexp_f32 v124, v124, v126
	v_log_f32_e32 v124, v124
	s_nop 0
	v_mul_f32_e32 v126, 0x3f317217, v124
	v_fma_f32 v126, v124, s71, -v126
	v_fmac_f32_e32 v126, 0x3377d1cf, v124
	v_fmac_f32_e32 v126, 0x3f317217, v124
	v_cmp_lt_f32_e64 s[2:3], |v124|, s72
	s_nop 1
	v_cndmask_b32_e64 v124, v124, v126, s[2:3]
	v_cndmask_b32_e32 v126, 0, v115, vcc
	v_sub_f32_e32 v124, v124, v126
	ds_read_b128 v[152:155], v63 offset:64
	ds_read_b128 v[156:159], v63 offset:80
	ds_read_b128 v[160:163], v63 offset:96
	ds_read_b128 v[164:167], v63 offset:112
	ds_read_b128 v[168:171], v63 offset:128
	ds_read_b128 v[172:175], v63 offset:144
	ds_read_b128 v[176:179], v63 offset:160
	ds_read_b128 v[180:183], v63 offset:176
	ds_read_b128 v[184:187], v63 offset:192
	ds_read_b128 v[188:191], v63 offset:208
	ds_read_b128 v[192:195], v63 offset:224
	ds_read_b128 v[196:199], v63 offset:240
	ds_read_b128 v[200:203], v63 offset:256
	v_sub_f32_e32 v124, v125, v124
	s_mov_b32 s2, 0x3d800000
	v_fma_f32 v124, v124, s2, 0
	s_waitcnt lgkmcnt(12)
; DI float log_sigmoid_(float x) { return fminf(x, 0.f) - __logf(1.f + __expf(-fabsf(x))); }
; DI void gla_pre_item(Frame& F, int item, PreRegs& R, int nxt) {
;     ...
;     for (int i = 0; i < 16; ++i) { const int t = 16 * tq + i; float x = b2;
; #pragma unroll
;         for (int r = 0; r < 16; ++r) x += GA[t * 16 + r] * w2r[r];
;         run += log_sigmoid_(x) * (1.f / 16.f); cum[i] = run; }
	v_fma_f32 v125, v120, v152, v38
	v_fmac_f32_e32 v125, v121, v153
	v_fmac_f32_e32 v125, v122, v154
	v_fmac_f32_e32 v125, v123, v155
	ds_read_b128 v[204:207], v63 offset:272
	s_waitcnt lgkmcnt(12)
	v_fmac_f32_e32 v125, v10, v156
	v_fmac_f32_e32 v125, v11, v157
	v_fmac_f32_e32 v125, v118, v158
	v_fmac_f32_e32 v125, v119, v159
	ds_read_b128 v[208:211], v63 offset:288
	s_waitcnt lgkmcnt(12)
	v_fmac_f32_e32 v125, v19, v160
	v_fmac_f32_e32 v125, v103, v161
	v_fmac_f32_e32 v125, v116, v162
	v_fmac_f32_e32 v125, v117, v163
	ds_read_b128 v[212:215], v63 offset:304
	s_waitcnt lgkmcnt(12)
	v_fmac_f32_e32 v125, v7, v164
	v_fmac_f32_e32 v125, v6, v165
	v_fmac_f32_e32 v125, v9, v166
	v_fmac_f32_e32 v125, v8, v167
	v_min_f32_e32 v126, 0, v125
	v_mul_f32_e64 v125, |v125|, s69
	v_exp_f32_e32 v125, v125
	s_nop 0
	v_add_f32_e32 v125, 1.0, v125
	v_cmp_gt_f32_e32 vcc, s70, v125
	s_nop 1
	v_cndmask_b32_e64 v127, 0, 32, vcc
	v_ldexp_f32 v125, v125, v127
	v_log_f32_e32 v125, v125
	s_nop 0
	v_mul_f32_e32 v127, 0x3f317217, v125
	v_fma_f32 v127, v125, s71, -v127
	v_fmac_f32_e32 v127, 0x3377d1cf, v125
	v_fmac_f32_e32 v127, 0x3f317217, v125
	v_cmp_lt_f32_e64 s[2:3], |v125|, s72
	s_nop 1
	v_cndmask_b32_e64 v125, v125, v127, s[2:3]
	v_cndmask_b32_e32 v127, 0, v115, vcc
	v_sub_f32_e32 v125, v125, v127
	v_sub_f32_e32 v125, v126, v125
	ds_read_b128 v[152:155], v63 offset:320
	v_fmamk_f32 v125, v125, 0x3d800000, v124
	s_waitcnt lgkmcnt(12)
	v_fma_f32 v130, v120, v168, v38
	v_fmac_f32_e32 v130, v121, v169
	v_fmac_f32_e32 v130, v122, v170
	v_fmac_f32_e32 v130, v123, v171
	ds_read_b128 v[156:159], v63 offset:336
	s_waitcnt lgkmcnt(12)
	v_fmac_f32_e32 v130, v10, v172
	v_fmac_f32_e32 v130, v11, v173
	v_fmac_f32_e32 v130, v118, v174
	v_fmac_f32_e32 v130, v119, v175
	ds_read_b128 v[160:163], v63 offset:352
	s_waitcnt lgkmcnt(12)
	v_fmac_f32_e32 v130, v19, v176
	v_fmac_f32_e32 v130, v103, v177
	v_fmac_f32_e32 v130, v116, v178
	v_fmac_f32_e32 v130, v117, v179
	ds_read_b128 v[164:167], v63 offset:368
	s_waitcnt lgkmcnt(12)
	v_fmac_f32_e32 v130, v7, v180
	v_fmac_f32_e32 v130, v6, v181
	v_fmac_f32_e32 v130, v9, v182
	v_fmac_f32_e32 v130, v8, v183
	v_mul_f32_e64 v127, |v130|, s69
	v_exp_f32_e32 v127, v127
	v_min_f32_e32 v126, 0, v130
	v_add_f32_e32 v127, 1.0, v127
	v_cmp_gt_f32_e32 vcc, s70, v127
	s_nop 1
	v_cndmask_b32_e64 v128, 0, 32, vcc
	v_ldexp_f32 v127, v127, v128
	v_log_f32_e32 v127, v127
	s_nop 0
	v_mul_f32_e32 v128, 0x3f317217, v127
	v_fma_f32 v128, v127, s71, -v128
	v_fmac_f32_e32 v128, 0x3377d1cf, v127
	v_fmac_f32_e32 v128, 0x3f317217, v127
	v_cmp_lt_f32_e64 s[2:3], |v127|, s72
	s_nop 1
	v_cndmask_b32_e64 v127, v127, v128, s[2:3]
	v_cndmask_b32_e32 v128, 0, v115, vcc
	v_sub_f32_e32 v127, v127, v128
	ds_read_b128 v[168:171], v63 offset:384
	v_sub_f32_e32 v126, v126, v127
	v_fmamk_f32 v126, v126, 0x3d800000, v125
	s_waitcnt lgkmcnt(12)
	v_fma_f32 v127, v120, v184, v38
	v_fmac_f32_e32 v127, v121, v185
	v_fmac_f32_e32 v127, v122, v186
	v_fmac_f32_e32 v127, v123, v187
	ds_read_b128 v[172:175], v63 offset:400
	s_waitcnt lgkmcnt(12)
	v_fmac_f32_e32 v127, v10, v188
	v_fmac_f32_e32 v127, v11, v189
	v_fmac_f32_e32 v127, v118, v190
	v_fmac_f32_e32 v127, v119, v191
	ds_read_b128 v[176:179], v63 offset:416
	s_waitcnt lgkmcnt(12)
	v_fmac_f32_e32 v127, v19, v192
	v_fmac_f32_e32 v127, v103, v193
	v_fmac_f32_e32 v127, v116, v194
	v_fmac_f32_e32 v127, v117, v195
	ds_read_b128 v[180:183], v63 offset:432
	s_waitcnt lgkmcnt(12)
	v_fmac_f32_e32 v127, v7, v196
	v_fmac_f32_e32 v127, v6, v197
	v_fmac_f32_e32 v127, v9, v198
	v_fmac_f32_e32 v127, v8, v199
	v_min_f32_e32 v128, 0, v127
	v_mul_f32_e64 v127, |v127|, s69
	v_exp_f32_e32 v127, v127
	s_nop 0
	v_add_f32_e32 v127, 1.0, v127
	v_cmp_gt_f32_e32 vcc, s70, v127
	s_nop 1
	v_cndmask_b32_e64 v129, 0, 32, vcc
	v_ldexp_f32 v127, v127, v129
	v_log_f32_e32 v127, v127
	s_nop 0
	v_mul_f32_e32 v129, 0x3f317217, v127
	v_fma_f32 v129, v127, s71, -v129
	v_fmac_f32_e32 v129, 0x3377d1cf, v127
	v_fmac_f32_e32 v129, 0x3f317217, v127
	v_cmp_lt_f32_e64 s[2:3], |v127|, s72
	s_nop 1
	v_cndmask_b32_e64 v127, v127, v129, s[2:3]
	v_cndmask_b32_e32 v129, 0, v115, vcc
	v_sub_f32_e32 v127, v127, v129
	v_sub_f32_e32 v127, v128, v127
	ds_read_b128 v[184:187], v63 offset:448
	v_fmamk_f32 v127, v127, 0x3d800000, v126
	s_waitcnt lgkmcnt(12)
	v_fma_f32 v132, v120, v200, v38
	v_fmac_f32_e32 v132, v121, v201
	v_fmac_f32_e32 v132, v122, v202
	v_fmac_f32_e32 v132, v123, v203
	ds_read_b128 v[188:191], v63 offset:464
	s_waitcnt lgkmcnt(12)
	v_fmac_f32_e32 v132, v10, v204
	v_fmac_f32_e32 v132, v11, v205
	v_fmac_f32_e32 v132, v118, v206
	v_fmac_f32_e32 v132, v119, v207
	ds_read_b128 v[192:195], v63 offset:480
	s_waitcnt lgkmcnt(12)
	v_fmac_f32_e32 v132, v19, v208
	v_fmac_f32_e32 v132, v103, v209
	v_fmac_f32_e32 v132, v116, v210
	v_fmac_f32_e32 v132, v117, v211
	ds_read_b128 v[196:199], v63 offset:496
	s_waitcnt lgkmcnt(12)
	v_fmac_f32_e32 v132, v7, v212
	v_fmac_f32_e32 v132, v6, v213
	v_fmac_f32_e32 v132, v9, v214
	v_fmac_f32_e32 v132, v8, v215
	v_mul_f32_e64 v129, |v132|, s69
	v_exp_f32_e32 v129, v129
	v_min_f32_e32 v128, 0, v132
	v_add_f32_e32 v129, 1.0, v129
	v_cmp_gt_f32_e32 vcc, s70, v129
	s_nop 1
	v_cndmask_b32_e64 v130, 0, 32, vcc
	v_ldexp_f32 v129, v129, v130
	v_log_f32_e32 v129, v129
	s_nop 0
	v_mul_f32_e32 v130, 0x3f317217, v129
	v_fma_f32 v130, v129, s71, -v130
	v_fmac_f32_e32 v130, 0x3377d1cf, v129
	v_fmac_f32_e32 v130, 0x3f317217, v129
	v_cmp_lt_f32_e64 s[2:3], |v129|, s72
	s_nop 1
	v_cndmask_b32_e64 v129, v129, v130, s[2:3]
	v_cndmask_b32_e32 v130, 0, v115, vcc
	v_sub_f32_e32 v129, v129, v130
	ds_read_b128 v[200:203], v63 offset:512
	v_sub_f32_e32 v128, v128, v129
	v_fmamk_f32 v128, v128, 0x3d800000, v127
	s_waitcnt lgkmcnt(12)
; DI float log_sigmoid_(float x) { return fminf(x, 0.f) - __logf(1.f + __expf(-fabsf(x))); }
; DI void gla_pre_item(Frame& F, int item, PreRegs& R, int nxt) {
;     ...
;     for (int i = 0; i < 16; ++i) { const int t = 16 * tq + i; float x = b2;
; #pragma unroll
;         for (int r = 0; r < 16; ++r) x += GA[t * 16 + r] * w2r[r];
;         run += log_sigmoid_(x) * (1.f / 16.f); cum[i] = run; }
	v_fma_f32 v129, v120, v152, v38
	v_fmac_f32_e32 v129, v121, v153
	v_fmac_f32_e32 v129, v122, v154
	v_fmac_f32_e32 v129, v123, v155
	ds_read_b128 v[204:207], v63 offset:528
	s_waitcnt lgkmcnt(12)
	v_fmac_f32_e32 v129, v10, v156
	v_fmac_f32_e32 v129, v11, v157
	v_fmac_f32_e32 v129, v118, v158
	v_fmac_f32_e32 v129, v119, v159
	ds_read_b128 v[208:211], v63 offset:544
	s_waitcnt lgkmcnt(12)
	v_fmac_f32_e32 v129, v19, v160
	v_fmac_f32_e32 v129, v103, v161
	v_fmac_f32_e32 v129, v116, v162
	v_fmac_f32_e32 v129, v117, v163
	ds_read_b128 v[212:215], v63 offset:560
	s_waitcnt lgkmcnt(12)
	v_fmac_f32_e32 v129, v7, v164
	v_fmac_f32_e32 v129, v6, v165
	v_fmac_f32_e32 v129, v9, v166
	v_fmac_f32_e32 v129, v8, v167
	v_min_f32_e32 v130, 0, v129
	v_mul_f32_e64 v129, |v129|, s69
	v_exp_f32_e32 v129, v129
	s_nop 0
	v_add_f32_e32 v129, 1.0, v129
	v_cmp_gt_f32_e32 vcc, s70, v129
	s_nop 1
	v_cndmask_b32_e64 v131, 0, 32, vcc
	v_ldexp_f32 v129, v129, v131
	v_log_f32_e32 v129, v129
	s_nop 0
	v_mul_f32_e32 v131, 0x3f317217, v129
	v_fma_f32 v131, v129, s71, -v131
	v_fmac_f32_e32 v131, 0x3377d1cf, v129
	v_fmac_f32_e32 v131, 0x3f317217, v129
	v_cmp_lt_f32_e64 s[2:3], |v129|, s72
	s_nop 1
	v_cndmask_b32_e64 v129, v129, v131, s[2:3]
	v_cndmask_b32_e32 v131, 0, v115, vcc
	v_sub_f32_e32 v129, v129, v131
	v_sub_f32_e32 v129, v130, v129
	ds_read_b128 v[152:155], v63 offset:576
	v_fmamk_f32 v129, v129, 0x3d800000, v128
	s_waitcnt lgkmcnt(12)
	v_fma_f32 v134, v120, v168, v38
	v_fmac_f32_e32 v134, v121, v169
	v_fmac_f32_e32 v134, v122, v170
	v_fmac_f32_e32 v134, v123, v171
	ds_read_b128 v[156:159], v63 offset:592
	s_waitcnt lgkmcnt(12)
	v_fmac_f32_e32 v134, v10, v172
	v_fmac_f32_e32 v134, v11, v173
	v_fmac_f32_e32 v134, v118, v174
	v_fmac_f32_e32 v134, v119, v175
	ds_read_b128 v[160:163], v63 offset:608
	s_waitcnt lgkmcnt(12)
	v_fmac_f32_e32 v134, v19, v176
	v_fmac_f32_e32 v134, v103, v177
	v_fmac_f32_e32 v134, v116, v178
	v_fmac_f32_e32 v134, v117, v179
	ds_read_b128 v[164:167], v63 offset:624
	s_waitcnt lgkmcnt(12)
	v_fmac_f32_e32 v134, v7, v180
	v_fmac_f32_e32 v134, v6, v181
	v_fmac_f32_e32 v134, v9, v182
	v_fmac_f32_e32 v134, v8, v183
	v_mul_f32_e64 v131, |v134|, s69
	v_exp_f32_e32 v131, v131
	v_min_f32_e32 v130, 0, v134
	v_add_f32_e32 v131, 1.0, v131
	v_cmp_gt_f32_e32 vcc, s70, v131
	s_nop 1
	v_cndmask_b32_e64 v132, 0, 32, vcc
	v_ldexp_f32 v131, v131, v132
	v_log_f32_e32 v131, v131
	s_nop 0
	v_mul_f32_e32 v132, 0x3f317217, v131
	v_fma_f32 v132, v131, s71, -v132
	v_fmac_f32_e32 v132, 0x3377d1cf, v131
	v_fmac_f32_e32 v132, 0x3f317217, v131
	v_cmp_lt_f32_e64 s[2:3], |v131|, s72
	s_nop 1
	v_cndmask_b32_e64 v131, v131, v132, s[2:3]
	v_cndmask_b32_e32 v132, 0, v115, vcc
	v_sub_f32_e32 v131, v131, v132
	ds_read_b128 v[168:171], v63 offset:640
	v_sub_f32_e32 v130, v130, v131
	v_fmamk_f32 v130, v130, 0x3d800000, v129
	s_waitcnt lgkmcnt(12)
	v_fma_f32 v131, v120, v184, v38
	v_fmac_f32_e32 v131, v121, v185
	v_fmac_f32_e32 v131, v122, v186
	v_fmac_f32_e32 v131, v123, v187
	ds_read_b128 v[172:175], v63 offset:656
	s_waitcnt lgkmcnt(12)
	v_fmac_f32_e32 v131, v10, v188
	v_fmac_f32_e32 v131, v11, v189
	v_fmac_f32_e32 v131, v118, v190
	v_fmac_f32_e32 v131, v119, v191
	ds_read_b128 v[176:179], v63 offset:672
	s_waitcnt lgkmcnt(12)
	v_fmac_f32_e32 v131, v19, v192
	v_fmac_f32_e32 v131, v103, v193
	v_fmac_f32_e32 v131, v116, v194
	v_fmac_f32_e32 v131, v117, v195
	ds_read_b128 v[180:183], v63 offset:688
	s_waitcnt lgkmcnt(12)
	v_fmac_f32_e32 v131, v7, v196
	v_fmac_f32_e32 v131, v6, v197
	v_fmac_f32_e32 v131, v9, v198
	v_fmac_f32_e32 v131, v8, v199
	v_min_f32_e32 v132, 0, v131
	v_mul_f32_e64 v131, |v131|, s69
	v_exp_f32_e32 v131, v131
	s_nop 0
	v_add_f32_e32 v131, 1.0, v131
	v_cmp_gt_f32_e32 vcc, s70, v131
	s_nop 1
	v_cndmask_b32_e64 v133, 0, 32, vcc
	v_ldexp_f32 v131, v131, v133
	v_log_f32_e32 v131, v131
	s_nop 0
	v_mul_f32_e32 v133, 0x3f317217, v131
	v_fma_f32 v133, v131, s71, -v133
	v_fmac_f32_e32 v133, 0x3377d1cf, v131
	v_fmac_f32_e32 v133, 0x3f317217, v131
	v_cmp_lt_f32_e64 s[2:3], |v131|, s72
	s_nop 1
	v_cndmask_b32_e64 v131, v131, v133, s[2:3]
	v_cndmask_b32_e32 v133, 0, v115, vcc
	v_sub_f32_e32 v131, v131, v133
	v_sub_f32_e32 v131, v132, v131
	ds_read_b128 v[184:187], v63 offset:704
	v_fmamk_f32 v131, v131, 0x3d800000, v130
	s_waitcnt lgkmcnt(12)
	v_fma_f32 v136, v120, v200, v38
	v_fmac_f32_e32 v136, v121, v201
	v_fmac_f32_e32 v136, v122, v202
	v_fmac_f32_e32 v136, v123, v203
	ds_read_b128 v[188:191], v63 offset:720
	s_waitcnt lgkmcnt(12)
	v_fmac_f32_e32 v136, v10, v204
	v_fmac_f32_e32 v136, v11, v205
	v_fmac_f32_e32 v136, v118, v206
	v_fmac_f32_e32 v136, v119, v207
	ds_read_b128 v[192:195], v63 offset:736
	s_waitcnt lgkmcnt(12)
	v_fmac_f32_e32 v136, v19, v208
	v_fmac_f32_e32 v136, v103, v209
	v_fmac_f32_e32 v136, v116, v210
	v_fmac_f32_e32 v136, v117, v211
	ds_read_b128 v[196:199], v63 offset:752
	s_waitcnt lgkmcnt(12)
	v_fmac_f32_e32 v136, v7, v212
	v_fmac_f32_e32 v136, v6, v213
	v_fmac_f32_e32 v136, v9, v214
	v_fmac_f32_e32 v136, v8, v215
	v_mul_f32_e64 v133, |v136|, s69
	v_exp_f32_e32 v133, v133
	v_min_f32_e32 v132, 0, v136
	v_add_f32_e32 v133, 1.0, v133
	v_cmp_gt_f32_e32 vcc, s70, v133
	s_nop 1
	v_cndmask_b32_e64 v134, 0, 32, vcc
	v_ldexp_f32 v133, v133, v134
	v_log_f32_e32 v133, v133
	s_nop 0
	v_mul_f32_e32 v134, 0x3f317217, v133
	v_fma_f32 v134, v133, s71, -v134
	v_fmac_f32_e32 v134, 0x3377d1cf, v133
	v_fmac_f32_e32 v134, 0x3f317217, v133
	v_cmp_lt_f32_e64 s[2:3], |v133|, s72
	s_nop 1
	v_cndmask_b32_e64 v133, v133, v134, s[2:3]
	v_cndmask_b32_e32 v134, 0, v115, vcc
	v_sub_f32_e32 v133, v133, v134
	ds_read_b128 v[200:203], v63 offset:768
	v_sub_f32_e32 v132, v132, v133
	v_fmamk_f32 v132, v132, 0x3d800000, v131
	s_waitcnt lgkmcnt(12)
; DI float log_sigmoid_(float x) { return fminf(x, 0.f) - __logf(1.f + __expf(-fabsf(x))); }
; DI void gla_pre_item(Frame& F, int item, PreRegs& R, int nxt) {
;     ...
;     for (int i = 0; i < 16; ++i) { const int t = 16 * tq + i; float x = b2;
; #pragma unroll
;         for (int r = 0; r < 16; ++r) x += GA[t * 16 + r] * w2r[r];
;         run += log_sigmoid_(x) * (1.f / 16.f); cum[i] = run; }
	v_fma_f32 v133, v120, v152, v38
	v_fmac_f32_e32 v133, v121, v153
	v_fmac_f32_e32 v133, v122, v154
	v_fmac_f32_e32 v133, v123, v155
	ds_read_b128 v[204:207], v63 offset:784
	s_waitcnt lgkmcnt(12)
	v_fmac_f32_e32 v133, v10, v156
	v_fmac_f32_e32 v133, v11, v157
	v_fmac_f32_e32 v133, v118, v158
	v_fmac_f32_e32 v133, v119, v159
	ds_read_b128 v[208:211], v63 offset:800
	s_waitcnt lgkmcnt(12)
	v_fmac_f32_e32 v133, v19, v160
	v_fmac_f32_e32 v133, v103, v161
	v_fmac_f32_e32 v133, v116, v162
	v_fmac_f32_e32 v133, v117, v163
	ds_read_b128 v[212:215], v63 offset:816
	s_waitcnt lgkmcnt(12)
	v_fmac_f32_e32 v133, v7, v164
	v_fmac_f32_e32 v133, v6, v165
	v_fmac_f32_e32 v133, v9, v166
	v_fmac_f32_e32 v133, v8, v167
	v_min_f32_e32 v134, 0, v133
	v_mul_f32_e64 v133, |v133|, s69
	v_exp_f32_e32 v133, v133
	s_nop 0
	v_add_f32_e32 v133, 1.0, v133
	v_cmp_gt_f32_e32 vcc, s70, v133
	s_nop 1
	v_cndmask_b32_e64 v135, 0, 32, vcc
	v_ldexp_f32 v133, v133, v135
	v_log_f32_e32 v133, v133
	s_nop 0
	v_mul_f32_e32 v135, 0x3f317217, v133
	v_fma_f32 v135, v133, s71, -v135
	v_fmac_f32_e32 v135, 0x3377d1cf, v133
	v_fmac_f32_e32 v135, 0x3f317217, v133
	v_cmp_lt_f32_e64 s[2:3], |v133|, s72
	s_nop 1
	v_cndmask_b32_e64 v133, v133, v135, s[2:3]
	v_cndmask_b32_e32 v135, 0, v115, vcc
	v_sub_f32_e32 v133, v133, v135
	v_sub_f32_e32 v133, v134, v133
	ds_read_b128 v[152:155], v63 offset:832
	v_fmamk_f32 v133, v133, 0x3d800000, v132
	s_waitcnt lgkmcnt(12)
	v_fma_f32 v138, v120, v168, v38
	v_fmac_f32_e32 v138, v121, v169
	v_fmac_f32_e32 v138, v122, v170
	v_fmac_f32_e32 v138, v123, v171
	ds_read_b128 v[156:159], v63 offset:848
	s_waitcnt lgkmcnt(12)
	v_fmac_f32_e32 v138, v10, v172
	v_fmac_f32_e32 v138, v11, v173
	v_fmac_f32_e32 v138, v118, v174
	v_fmac_f32_e32 v138, v119, v175
	ds_read_b128 v[160:163], v63 offset:864
	s_waitcnt lgkmcnt(12)
	v_fmac_f32_e32 v138, v19, v176
	v_fmac_f32_e32 v138, v103, v177
	v_fmac_f32_e32 v138, v116, v178
	v_fmac_f32_e32 v138, v117, v179
	ds_read_b128 v[164:167], v63 offset:880
	s_waitcnt lgkmcnt(12)
	v_fmac_f32_e32 v138, v7, v180
	v_fmac_f32_e32 v138, v6, v181
	v_fmac_f32_e32 v138, v9, v182
	v_fmac_f32_e32 v138, v8, v183
	v_mul_f32_e64 v135, |v138|, s69
	v_exp_f32_e32 v135, v135
	v_min_f32_e32 v134, 0, v138
	v_add_f32_e32 v135, 1.0, v135
	v_cmp_gt_f32_e32 vcc, s70, v135
	s_nop 1
	v_cndmask_b32_e64 v136, 0, 32, vcc
	v_ldexp_f32 v135, v135, v136
	v_log_f32_e32 v135, v135
	s_nop 0
	v_mul_f32_e32 v136, 0x3f317217, v135
	v_fma_f32 v136, v135, s71, -v136
	v_fmac_f32_e32 v136, 0x3377d1cf, v135
	v_fmac_f32_e32 v136, 0x3f317217, v135
	v_cmp_lt_f32_e64 s[2:3], |v135|, s72
	s_nop 1
	v_cndmask_b32_e64 v135, v135, v136, s[2:3]
	v_cndmask_b32_e32 v136, 0, v115, vcc
	v_sub_f32_e32 v135, v135, v136
	ds_read_b128 v[168:171], v63 offset:896
	v_sub_f32_e32 v134, v134, v135
	v_fmamk_f32 v134, v134, 0x3d800000, v133
	s_waitcnt lgkmcnt(12)
	v_fma_f32 v135, v120, v184, v38
	v_fmac_f32_e32 v135, v121, v185
	v_fmac_f32_e32 v135, v122, v186
	v_fmac_f32_e32 v135, v123, v187
	ds_read_b128 v[172:175], v63 offset:912
	s_waitcnt lgkmcnt(12)
	v_fmac_f32_e32 v135, v10, v188
	v_fmac_f32_e32 v135, v11, v189
	v_fmac_f32_e32 v135, v118, v190
	v_fmac_f32_e32 v135, v119, v191
	ds_read_b128 v[176:179], v63 offset:928
	s_waitcnt lgkmcnt(12)
	v_fmac_f32_e32 v135, v19, v192
	v_fmac_f32_e32 v135, v103, v193
	v_fmac_f32_e32 v135, v116, v194
	v_fmac_f32_e32 v135, v117, v195
	ds_read_b128 v[180:183], v63 offset:944
	s_waitcnt lgkmcnt(12)
	v_fmac_f32_e32 v135, v7, v196
	v_fmac_f32_e32 v135, v6, v197
	v_fmac_f32_e32 v135, v9, v198
	v_fmac_f32_e32 v135, v8, v199
	v_min_f32_e32 v136, 0, v135
	v_mul_f32_e64 v135, |v135|, s69
	v_exp_f32_e32 v135, v135
	s_nop 0
	v_add_f32_e32 v135, 1.0, v135
	v_cmp_gt_f32_e32 vcc, s70, v135
	s_nop 1
	v_cndmask_b32_e64 v137, 0, 32, vcc
	v_ldexp_f32 v135, v135, v137
	v_log_f32_e32 v135, v135
	s_nop 0
	v_mul_f32_e32 v137, 0x3f317217, v135
	v_fma_f32 v137, v135, s71, -v137
	v_fmac_f32_e32 v137, 0x3377d1cf, v135
	v_fmac_f32_e32 v137, 0x3f317217, v135
	v_cmp_lt_f32_e64 s[2:3], |v135|, s72
	s_nop 1
	v_cndmask_b32_e64 v135, v135, v137, s[2:3]
	v_cndmask_b32_e32 v137, 0, v115, vcc
	v_sub_f32_e32 v135, v135, v137
	v_sub_f32_e32 v135, v136, v135
	ds_read_b128 v[184:187], v63 offset:960
	v_fmamk_f32 v135, v135, 0x3d800000, v134
	s_waitcnt lgkmcnt(12)
	v_fma_f32 v140, v120, v200, v38
	v_fmac_f32_e32 v140, v121, v201
	v_fmac_f32_e32 v140, v122, v202
	v_fmac_f32_e32 v140, v123, v203
	ds_read_b128 v[188:191], v63 offset:976
	s_waitcnt lgkmcnt(12)
	v_fmac_f32_e32 v140, v10, v204
	v_fmac_f32_e32 v140, v11, v205
	v_fmac_f32_e32 v140, v118, v206
	v_fmac_f32_e32 v140, v119, v207
	ds_read_b128 v[192:195], v63 offset:992
	s_waitcnt lgkmcnt(12)
	v_fmac_f32_e32 v140, v19, v208
	v_fmac_f32_e32 v140, v103, v209
	v_fmac_f32_e32 v140, v116, v210
	v_fmac_f32_e32 v140, v117, v211
	ds_read_b128 v[196:199], v63 offset:1008
	s_waitcnt lgkmcnt(12)
; DI float log_sigmoid_(float x) { return fminf(x, 0.f) - __logf(1.f + __expf(-fabsf(x))); }
; DI void gla_pre_item(Frame& F, int item, PreRegs& R, int nxt) {
;     ...
;     for (int i = 0; i < 16; ++i) { const int t = 16 * tq + i; float x = b2;
; #pragma unroll
;         for (int r = 0; r < 16; ++r) x += GA[t * 16 + r] * w2r[r];
;         run += log_sigmoid_(x) * (1.f / 16.f); cum[i] = run; }
;     PART[tq * 128 + kk] = run;
;     __syncthreads();
;     float off = 0.f;
; #pragma unroll
;     for (int j = 0; j < 3; ++j) off += (j < tq) ? PART[j * 128 + kk] : 0.f;
	v_fmac_f32_e32 v140, v7, v212
	v_fmac_f32_e32 v140, v6, v213
	v_fmac_f32_e32 v140, v9, v214
	v_fmac_f32_e32 v140, v8, v215
	v_mul_f32_e64 v137, |v140|, s69
	v_exp_f32_e32 v137, v137
	v_min_f32_e32 v136, 0, v140
	v_add_f32_e32 v137, 1.0, v137
	v_cmp_gt_f32_e32 vcc, s70, v137
	s_nop 1
	v_cndmask_b32_e64 v138, 0, 32, vcc
	v_ldexp_f32 v137, v137, v138
	v_log_f32_e32 v137, v137
	s_nop 0
	v_mul_f32_e32 v138, 0x3f317217, v137
	v_fma_f32 v138, v137, s71, -v138
	v_fmac_f32_e32 v138, 0x3377d1cf, v137
	v_fmac_f32_e32 v138, 0x3f317217, v137
	v_cmp_lt_f32_e64 s[2:3], |v137|, s72
	s_nop 1
	v_cndmask_b32_e64 v137, v137, v138, s[2:3]
	v_cndmask_b32_e32 v138, 0, v115, vcc
	v_sub_f32_e32 v137, v137, v138
	s_nop 0
	v_sub_f32_e32 v136, v136, v137
	v_fmamk_f32 v136, v136, 0x3d800000, v135
	s_waitcnt lgkmcnt(11)
	v_fma_f32 v137, v120, v152, v38
	v_fmac_f32_e32 v137, v121, v153
	v_fmac_f32_e32 v137, v122, v154
	v_fmac_f32_e32 v137, v123, v155
	s_nop 0
	s_waitcnt lgkmcnt(10)
	v_fmac_f32_e32 v137, v10, v156
	v_fmac_f32_e32 v137, v11, v157
	v_fmac_f32_e32 v137, v118, v158
	v_fmac_f32_e32 v137, v119, v159
	s_nop 0
	s_waitcnt lgkmcnt(9)
	v_fmac_f32_e32 v137, v19, v160
	v_fmac_f32_e32 v137, v103, v161
	v_fmac_f32_e32 v137, v116, v162
	v_fmac_f32_e32 v137, v117, v163
	s_nop 0
	s_waitcnt lgkmcnt(8)
	v_fmac_f32_e32 v137, v7, v164
	v_fmac_f32_e32 v137, v6, v165
	v_fmac_f32_e32 v137, v9, v166
	v_fmac_f32_e32 v137, v8, v167
	v_min_f32_e32 v138, 0, v137
	v_mul_f32_e64 v137, |v137|, s69
	v_exp_f32_e32 v137, v137
	s_nop 0
	v_add_f32_e32 v137, 1.0, v137
	v_cmp_gt_f32_e32 vcc, s70, v137
	s_nop 1
	v_cndmask_b32_e64 v139, 0, 32, vcc
	v_ldexp_f32 v137, v137, v139
	v_log_f32_e32 v137, v137
	s_nop 0
	v_mul_f32_e32 v139, 0x3f317217, v137
	v_fma_f32 v139, v137, s71, -v139
	v_fmac_f32_e32 v139, 0x3377d1cf, v137
	v_fmac_f32_e32 v139, 0x3f317217, v137
	v_cmp_lt_f32_e64 s[2:3], |v137|, s72
	s_nop 1
	v_cndmask_b32_e64 v137, v137, v139, s[2:3]
	v_cndmask_b32_e32 v139, 0, v115, vcc
	v_sub_f32_e32 v137, v137, v139
	v_sub_f32_e32 v137, v138, v137
	s_nop 0
	v_fmamk_f32 v137, v137, 0x3d800000, v136
	s_waitcnt lgkmcnt(7)
	v_fma_f32 v142, v120, v168, v38
	v_fmac_f32_e32 v142, v121, v169
	v_fmac_f32_e32 v142, v122, v170
	v_fmac_f32_e32 v142, v123, v171
	s_nop 0
	s_waitcnt lgkmcnt(6)
	v_fmac_f32_e32 v142, v10, v172
	v_fmac_f32_e32 v142, v11, v173
	v_fmac_f32_e32 v142, v118, v174
	v_fmac_f32_e32 v142, v119, v175
	s_nop 0
	s_waitcnt lgkmcnt(5)
	v_fmac_f32_e32 v142, v19, v176
	v_fmac_f32_e32 v142, v103, v177
	v_fmac_f32_e32 v142, v116, v178
	v_fmac_f32_e32 v142, v117, v179
	s_nop 0
	s_waitcnt lgkmcnt(4)
	v_fmac_f32_e32 v142, v7, v180
	v_fmac_f32_e32 v142, v6, v181
	v_fmac_f32_e32 v142, v9, v182
	v_fmac_f32_e32 v142, v8, v183
	v_mul_f32_e64 v139, |v142|, s69
	v_exp_f32_e32 v139, v139
	v_min_f32_e32 v138, 0, v142
	v_add_f32_e32 v139, 1.0, v139
	v_cmp_gt_f32_e32 vcc, s70, v139
	s_nop 1
	v_cndmask_b32_e64 v140, 0, 32, vcc
	v_ldexp_f32 v139, v139, v140
	v_log_f32_e32 v139, v139
	s_nop 0
	v_mul_f32_e32 v140, 0x3f317217, v139
	v_fma_f32 v140, v139, s71, -v140
	v_fmac_f32_e32 v140, 0x3377d1cf, v139
	v_fmac_f32_e32 v140, 0x3f317217, v139
	v_cmp_lt_f32_e64 s[2:3], |v139|, s72
	s_nop 1
	v_cndmask_b32_e64 v139, v139, v140, s[2:3]
	v_cndmask_b32_e32 v140, 0, v115, vcc
	v_sub_f32_e32 v139, v139, v140
	s_nop 0
	v_sub_f32_e32 v138, v138, v139
	v_fmamk_f32 v138, v138, 0x3d800000, v137
	s_waitcnt lgkmcnt(3)
	v_fmac_f32_e32 v38, v120, v184
	v_fmac_f32_e32 v38, v121, v185
	v_fmac_f32_e32 v38, v122, v186
	v_fmac_f32_e32 v38, v123, v187
	s_nop 0
	s_waitcnt lgkmcnt(2)
	v_fmac_f32_e32 v38, v10, v188
	v_fmac_f32_e32 v38, v11, v189
	v_fmac_f32_e32 v38, v118, v190
	v_fmac_f32_e32 v38, v119, v191
	s_nop 0
	s_waitcnt lgkmcnt(1)
	v_fmac_f32_e32 v38, v19, v192
	v_fmac_f32_e32 v38, v103, v193
	v_fmac_f32_e32 v38, v116, v194
	v_fmac_f32_e32 v38, v117, v195
	s_nop 0
	s_waitcnt lgkmcnt(0)
	v_fmac_f32_e32 v38, v7, v196
	v_fmac_f32_e32 v38, v6, v197
	v_fmac_f32_e32 v38, v9, v198
	v_fmac_f32_e32 v38, v8, v199
	v_mul_f32_e64 v7, |v38|, s69
	v_exp_f32_e32 v7, v7
	v_min_f32_e32 v6, 0, v38
	v_add_f32_e32 v7, 1.0, v7
	v_cmp_gt_f32_e32 vcc, s70, v7
	s_nop 1
	v_cndmask_b32_e64 v8, 0, 32, vcc
	v_ldexp_f32 v7, v7, v8
	v_log_f32_e32 v7, v7
	s_nop 0
	v_mul_f32_e32 v8, 0x3f317217, v7
	v_fma_f32 v8, v7, s71, -v8
	v_fmac_f32_e32 v8, 0x3377d1cf, v7
	v_fmac_f32_e32 v8, 0x3f317217, v7
	v_cmp_lt_f32_e64 s[2:3], |v7|, s72
	s_nop 1
	v_cndmask_b32_e64 v7, v7, v8, s[2:3]
	v_cndmask_b32_e32 v8, 0, v115, vcc
	v_sub_f32_e32 v7, v7, v8
	v_sub_f32_e32 v6, v6, v7
	v_fmamk_f32 v6, v6, 0x3d800000, v138
	v_mov_b32_e32 v7, 0
	v_mov_b32_e32 v8, 0
	ds_write_b32 v65, v6
	s_waitcnt lgkmcnt(0)
	s_barrier
	s_and_saveexec_b64 s[2:3], s[4:5]
	s_cbranch_execz .LBB0_1038
	ds_read_b32 v8, v67
	s_waitcnt lgkmcnt(0)
	v_add_f32_e32 v8, 0, v8
	s_or_b64 exec, exec, s[2:3]
	v_mov_b32_e32 v9, 0
	s_and_saveexec_b64 s[2:3], s[6:7]
	s_cbranch_execnz .LBB0_1039
